# context-row K-split epilogue of phases 7 and 10: the sixteen gate loads issued together up front into dead registers, counted vmcnt(15) instead of sixteen load-wait-store round trips
# baseline (speedup 1.0000x reference)
.LBB0_874:
	s_ashr_i32 s50, s48, 6
	s_bfe_u32 s67, s48, 0x10005
	s_mulk_i32 s50, 0x42
	s_or_b32 s50, s50, s67
	s_and_b32 s8, s48, 3
	s_bfe_u32 s49, s48, 0x30002
	s_mul_i32 s68, s50, 0x44000
	s_mul_hi_i32 s67, s50, 0x44000
	s_add_u32 s68, s2, s68
	s_addc_u32 s67, s3, s67
	s_lshl_b32 s8, s8, 9
	s_add_u32 s68, s68, s8
	s_mul_i32 s70, s49, 0x44000
	s_addc_u32 s69, s67, 0
	s_add_u32 s67, s4, s70
	v_lshl_add_u64 v[0:1], s[68:69], 0, v[10:11]
	s_addc_u32 s69, s5, 0
	s_add_u32 s68, s67, s8
	v_readfirstlane_b32 s66, v18
	s_addc_u32 s69, s69, 0
	v_readfirstlane_b32 s59, v19
	v_lshl_add_u64 v[0:1], v[0:1], 0, v[12:13]
	s_mov_b32 m0, s66
	v_lshl_add_u64 v[2:3], s[68:69], 0, v[14:15]
	s_waitcnt vmcnt(63) expcnt(7) lgkmcnt(15)
	s_barrier
	v_readfirstlane_b32 s60, v20
	global_load_lds_dwordx4 v[0:1], off
	v_lshl_add_u64 v[2:3], v[2:3], 0, v[12:13]
	s_mov_b32 m0, s59
	v_readfirstlane_b32 s61, v21
	v_lshl_add_u64 v[4:5], v[0:1], 0, s[10:11]
	global_load_lds_dwordx4 v[2:3], off
	s_mov_b32 m0, s60
	v_readfirstlane_b32 s62, v22
	v_lshl_add_u64 v[40:41], v[2:3], 0, s[10:11]
	global_load_lds_dwordx4 v[4:5], off
	s_mov_b32 m0, s61
	v_readfirstlane_b32 s63, v23
	v_lshl_add_u64 v[6:7], v[0:1], 0, s[12:13]
	global_load_lds_dwordx4 v[40:41], off
	s_mov_b32 m0, s62
	v_readfirstlane_b32 s64, v24
	v_lshl_add_u64 v[42:43], v[2:3], 0, s[12:13]
	global_load_lds_dwordx4 v[6:7], off
	s_mov_b32 m0, s63
	v_readfirstlane_b32 s65, v25
	v_lshl_add_u64 v[16:17], v[0:1], 0, s[14:15]
	global_load_lds_dwordx4 v[42:43], off
	s_mov_b32 m0, s64
	v_readfirstlane_b32 s58, v26
	v_lshl_add_u64 v[52:53], v[2:3], 0, s[14:15]
	global_load_lds_dwordx4 v[16:17], off
	s_mov_b32 m0, s65
	v_readfirstlane_b32 s51, v27
	v_lshl_add_u64 v[44:45], v[0:1], 0, s[16:17]
	global_load_lds_dwordx4 v[52:53], off
	s_mov_b32 m0, s58
	v_readfirstlane_b32 s52, v28
	v_lshl_add_u64 v[54:55], v[2:3], 0, s[16:17]
	s_waitcnt vmcnt(0) lgkmcnt(0)
	s_barrier
	ds_read_b128 v[4:7], v35 offset:16384
	ds_read_b128 v[40:43], v35 offset:18432
	global_load_lds_dwordx4 v[44:45], off
	s_mov_b32 m0, s51
	v_readfirstlane_b32 s53, v29
	v_lshl_add_u64 v[46:47], v[0:1], 0, s[18:19]
	global_load_lds_dwordx4 v[54:55], off
	s_mov_b32 m0, s52
	v_readfirstlane_b32 s54, v30
	v_lshl_add_u64 v[56:57], v[2:3], 0, s[18:19]
	global_load_lds_dwordx4 v[46:47], off
	s_mov_b32 m0, s53
	v_readfirstlane_b32 s55, v31
	v_lshl_add_u64 v[48:49], v[0:1], 0, s[20:21]
	global_load_lds_dwordx4 v[56:57], off
	s_mov_b32 m0, s54
	v_readfirstlane_b32 s56, v32
	v_lshl_add_u64 v[58:59], v[2:3], 0, s[20:21]
	global_load_lds_dwordx4 v[48:49], off
	s_mov_b32 m0, s55
	v_readfirstlane_b32 s57, v33
	v_lshl_add_u64 v[50:51], v[0:1], 0, s[22:23]
	global_load_lds_dwordx4 v[58:59], off
	s_mov_b32 m0, s56
	v_lshl_add_u64 v[60:61], v[2:3], 0, s[22:23]
	global_load_lds_dwordx4 v[50:51], off
	s_mov_b32 m0, s57
	v_lshl_add_u64 v[16:17], v[0:1], 0, s[24:25]
	global_load_lds_dwordx4 v[60:61], off
	ds_read_b128 v[44:47], v34
	ds_read_b128 v[48:51], v34 offset:2048
	ds_read_b128 v[56:59], v35 offset:20480
	ds_read_b128 v[64:67], v35 offset:22528
	ds_read_b128 v[72:75], v35 offset:24576
	ds_read_b128 v[84:87], v35 offset:26624
	ds_read_b128 v[92:95], v35 offset:28672
	ds_read_b128 v[100:103], v35 offset:30720
	s_waitcnt lgkmcnt(0)
	v_mfma_f32_16x16x32_bf16 v[52:55], v[4:7], v[44:47], 0
	ds_read_b128 v[108:111], v37 offset:16384
	ds_read_b128 v[112:115], v37 offset:18432
	s_mov_b32 m0, s66
	v_lshl_add_u64 v[154:155], v[2:3], 0, s[24:25]
	v_mfma_f32_16x16x32_bf16 v[60:63], v[40:43], v[44:47], 0
	v_lshl_add_u64 v[80:81], v[0:1], 0, s[26:27]
	v_lshl_add_u64 v[156:157], v[2:3], 0, s[26:27]
	v_lshl_add_u64 v[150:151], v[0:1], 0, s[28:29]
	v_mfma_f32_16x16x32_bf16 v[68:71], v[56:59], v[44:47], 0
	v_lshl_add_u64 v[158:159], v[2:3], 0, s[28:29]
	v_lshl_add_u64 v[152:153], v[0:1], 0, s[30:31]
	v_lshl_add_u64 v[160:161], v[2:3], 0, s[30:31]
	v_mfma_f32_16x16x32_bf16 v[76:79], v[64:67], v[44:47], 0
	v_lshl_add_u32 v39, s50, 7, v82
	v_lshl_or_b32 v8, s49, 9, v38
	v_mul_hi_i32 v83, v39, s44
	v_mfma_f32_16x16x32_bf16 v[88:91], v[72:75], v[44:47], 0
	v_lshrrev_b32_e32 v145, 31, v83
	v_lshrrev_b32_e32 v83, 11, v83
	v_add_u32_e32 v83, v83, v145
	v_mfma_f32_16x16x32_bf16 v[96:99], v[84:87], v[44:47], 0
	v_mov_b32_e32 v163, v9
	v_or_b32_e32 v162, 0x90, v8
	v_mov_b32_e32 v167, v9
	v_mfma_f32_16x16x32_bf16 v[104:107], v[92:95], v[44:47], 0
	v_or_b32_e32 v166, 0x110, v8
	s_add_i32 s48, s48, s33
	s_cmpk_lt_i32 s48, 0x80
	v_mfma_f32_16x16x32_bf16 v[44:47], v[100:103], v[44:47], 0
	v_mfma_f32_16x16x32_bf16 v[4:7], v[4:7], v[48:51], 0
	v_mfma_f32_16x16x32_bf16 v[40:43], v[40:43], v[48:51], 0
	v_mfma_f32_16x16x32_bf16 v[56:59], v[56:59], v[48:51], 0
	v_mfma_f32_16x16x32_bf16 v[64:67], v[64:67], v[48:51], 0
	v_mfma_f32_16x16x32_bf16 v[72:75], v[72:75], v[48:51], 0
	v_mfma_f32_16x16x32_bf16 v[84:87], v[84:87], v[48:51], 0
	v_mfma_f32_16x16x32_bf16 v[92:95], v[92:95], v[48:51], 0
	v_mfma_f32_16x16x32_bf16 v[48:51], v[100:103], v[48:51], 0
	ds_read_b128 v[100:103], v36
	ds_read_b128 v[116:119], v36 offset:2048
	ds_read_b128 v[120:123], v37 offset:20480
	ds_read_b128 v[124:127], v37 offset:22528
	ds_read_b128 v[128:131], v37 offset:24576
	ds_read_b128 v[132:135], v37 offset:26624
	ds_read_b128 v[136:139], v37 offset:28672
	ds_read_b128 v[140:143], v37 offset:30720
	s_waitcnt vmcnt(0) lgkmcnt(0)
	s_barrier
	global_load_lds_dwordx4 v[16:17], off
	s_mov_b32 m0, s59
	v_mfma_f32_16x16x32_bf16 v[52:55], v[108:111], v[100:103], v[52:55]
	v_lshl_add_u64 v[16:17], v[0:1], 0, s[34:35]
	v_mfma_f32_16x16x32_bf16 v[60:63], v[112:115], v[100:103], v[60:63]
	v_mfma_f32_16x16x32_bf16 v[68:71], v[120:123], v[100:103], v[68:71]
	v_mfma_f32_16x16x32_bf16 v[76:79], v[124:127], v[100:103], v[76:79]
	v_mfma_f32_16x16x32_bf16 v[88:91], v[128:131], v[100:103], v[88:91]
	v_mfma_f32_16x16x32_bf16 v[96:99], v[132:135], v[100:103], v[96:99]
	v_mfma_f32_16x16x32_bf16 v[104:107], v[136:139], v[100:103], v[104:107]
	v_mfma_f32_16x16x32_bf16 v[44:47], v[140:143], v[100:103], v[44:47]
	ds_read_b128 v[100:103], v35 offset:49152
	ds_read_b128 v[146:149], v35 offset:51200
	global_load_lds_dwordx4 v[154:155], off
	s_mov_b32 m0, s60
	v_mfma_f32_16x16x32_bf16 v[4:7], v[108:111], v[116:119], v[4:7]
	global_load_lds_dwordx4 v[80:81], off
	s_mov_b32 m0, s61
	v_mfma_f32_16x16x32_bf16 v[40:43], v[112:115], v[116:119], v[40:43]
	global_load_lds_dwordx4 v[156:157], off
	s_mov_b32 m0, s62
	v_mfma_f32_16x16x32_bf16 v[56:59], v[120:123], v[116:119], v[56:59]
	global_load_lds_dwordx4 v[150:151], off
	s_mov_b32 m0, s63
	v_mfma_f32_16x16x32_bf16 v[64:67], v[124:127], v[116:119], v[64:67]
	global_load_lds_dwordx4 v[158:159], off
	s_mov_b32 m0, s64
	v_mfma_f32_16x16x32_bf16 v[72:75], v[128:131], v[116:119], v[72:75]
	global_load_lds_dwordx4 v[152:153], off
	s_mov_b32 m0, s65
	v_mfma_f32_16x16x32_bf16 v[84:87], v[132:135], v[116:119], v[84:87]
	global_load_lds_dwordx4 v[160:161], off
	ds_read_b128 v[108:111], v34 offset:32768
	ds_read_b128 v[112:115], v34 offset:34816
	v_mfma_f32_16x16x32_bf16 v[92:95], v[136:139], v[116:119], v[92:95]
	ds_read_b128 v[120:123], v35 offset:55296
	ds_read_b128 v[124:127], v35 offset:57344
	ds_read_b128 v[128:131], v35 offset:59392
	v_mfma_f32_16x16x32_bf16 v[48:51], v[140:143], v[116:119], v[48:51]
	ds_read_b128 v[116:119], v35 offset:53248
	ds_read_b128 v[132:135], v35 offset:61440
	ds_read_b128 v[136:139], v35 offset:63488
	s_waitcnt lgkmcnt(0)
	v_mfma_f32_16x16x32_bf16 v[52:55], v[100:103], v[108:111], v[52:55]
	v_lshl_add_u64 v[80:81], v[0:1], 0, s[36:37]
	v_lshl_add_u64 v[150:151], v[2:3], 0, s[34:35]
	v_lshl_add_u64 v[152:153], v[2:3], 0, s[36:37]
	v_mfma_f32_16x16x32_bf16 v[60:63], v[146:149], v[108:111], v[60:63]
	v_lshl_add_u64 v[154:155], v[2:3], 0, s[38:39]
	v_lshl_add_u64 v[156:157], v[2:3], 0, s[40:41]
	s_mov_b32 m0, s58
	v_mfma_f32_16x16x32_bf16 v[68:71], v[116:119], v[108:111], v[68:71]
	v_mfma_f32_16x16x32_bf16 v[76:79], v[120:123], v[108:111], v[76:79]
	v_mfma_f32_16x16x32_bf16 v[88:91], v[124:127], v[108:111], v[88:91]
	v_mfma_f32_16x16x32_bf16 v[96:99], v[128:131], v[108:111], v[96:99]
	v_mfma_f32_16x16x32_bf16 v[104:107], v[132:135], v[108:111], v[104:107]
	v_mfma_f32_16x16x32_bf16 v[44:47], v[136:139], v[108:111], v[44:47]
	v_mfma_f32_16x16x32_bf16 v[4:7], v[100:103], v[112:115], v[4:7]
	v_mfma_f32_16x16x32_bf16 v[40:43], v[146:149], v[112:115], v[40:43]
	v_lshl_add_u64 v[146:147], v[0:1], 0, s[38:39]
	v_lshl_add_u64 v[148:149], v[0:1], 0, s[40:41]
	v_mfma_f32_16x16x32_bf16 v[56:59], v[116:119], v[112:115], v[56:59]
	v_mfma_f32_16x16x32_bf16 v[64:67], v[120:123], v[112:115], v[64:67]
	v_mfma_f32_16x16x32_bf16 v[72:75], v[124:127], v[112:115], v[72:75]
	v_mfma_f32_16x16x32_bf16 v[84:87], v[128:131], v[112:115], v[84:87]
	v_mfma_f32_16x16x32_bf16 v[0:3], v[132:135], v[112:115], v[92:95]
	s_nop 2
	ds_read_b128 v[92:95], v37 offset:49152
	ds_read_b128 v[100:103], v37 offset:51200
	v_mfma_f32_16x16x32_bf16 v[48:51], v[136:139], v[112:115], v[48:51]
	ds_read_b128 v[108:111], v36 offset:32768
	ds_read_b128 v[112:115], v36 offset:34816
	ds_read_b128 v[116:119], v37 offset:53248
	ds_read_b128 v[120:123], v37 offset:55296
	ds_read_b128 v[124:127], v37 offset:57344
	ds_read_b128 v[128:131], v37 offset:59392
	ds_read_b128 v[132:135], v37 offset:61440
	ds_read_b128 v[136:139], v37 offset:63488
	s_waitcnt vmcnt(0) lgkmcnt(0)
	s_barrier
	global_load_lds_dwordx4 v[16:17], off
	s_mov_b32 m0, s51
	v_mfma_f32_16x16x32_bf16 v[52:55], v[92:95], v[108:111], v[52:55]
	v_mul_hi_i32 v16, v39, s45
	v_lshrrev_b32_e32 v17, 31, v16
	v_ashrrev_i32_e32 v16, 11, v16
	v_mfma_f32_16x16x32_bf16 v[60:63], v[100:103], v[108:111], v[60:63]
	v_add_u32_e32 v16, v16, v17
	v_mad_i32_i24 v17, v16, s46, v39
	v_cmp_lt_i32_e32 vcc, s47, v17
	v_mfma_f32_16x16x32_bf16 v[68:71], v[116:119], v[108:111], v[68:71]
	s_nop 0
	v_cndmask_b32_e32 v16, 2, v16, vcc
	v_mul_hi_i32_i24_e32 v17, 0x6000, v16
	v_mfma_f32_16x16x32_bf16 v[76:79], v[120:123], v[108:111], v[76:79]
	v_mul_i32_i24_e32 v16, 0x6000, v16
	v_lshl_add_u64 v[16:17], s[94:95], 0, v[16:17]
	v_mfma_f32_16x16x32_bf16 v[88:91], v[124:127], v[108:111], v[88:91]
	v_mfma_f32_16x16x32_bf16 v[96:99], v[128:131], v[108:111], v[96:99]
	v_mfma_f32_16x16x32_bf16 v[104:107], v[132:135], v[108:111], v[104:107]
	v_mfma_f32_16x16x32_bf16 v[44:47], v[136:139], v[108:111], v[44:47]
	ds_read_b128 v[108:111], v35 offset:16384
	ds_read_b128 v[140:143], v35 offset:18432
	global_load_lds_dwordx4 v[150:151], off
	s_mov_b32 m0, s52
	v_mfma_f32_16x16x32_bf16 v[4:7], v[92:95], v[112:115], v[4:7]
	global_load_lds_dwordx4 v[80:81], off
	s_mov_b32 m0, s53
	v_mfma_f32_16x16x32_bf16 v[40:43], v[100:103], v[112:115], v[40:43]
	global_load_lds_dwordx4 v[152:153], off
	s_mov_b32 m0, s54
	v_mfma_f32_16x16x32_bf16 v[56:59], v[116:119], v[112:115], v[56:59]
	global_load_lds_dwordx4 v[146:147], off
	s_mov_b32 m0, s55
	v_mfma_f32_16x16x32_bf16 v[64:67], v[120:123], v[112:115], v[64:67]
	global_load_lds_dwordx4 v[154:155], off
	s_mov_b32 m0, s56
	v_mfma_f32_16x16x32_bf16 v[72:75], v[124:127], v[112:115], v[72:75]
	global_load_lds_dwordx4 v[148:149], off
	s_mov_b32 m0, s57
	v_mfma_f32_16x16x32_bf16 v[84:87], v[128:131], v[112:115], v[84:87]
	global_load_lds_dwordx4 v[156:157], off
	ds_read_b128 v[92:95], v34
	ds_read_b128 v[100:103], v34 offset:2048
	v_mfma_f32_16x16x32_bf16 v[0:3], v[132:135], v[112:115], v[0:3]
	ds_read_b128 v[116:119], v35 offset:22528
	ds_read_b128 v[120:123], v35 offset:24576
	ds_read_b128 v[124:127], v35 offset:26624
	v_mfma_f32_16x16x32_bf16 v[48:51], v[136:139], v[112:115], v[48:51]
	ds_read_b128 v[112:115], v35 offset:20480
	ds_read_b128 v[128:131], v35 offset:28672
	ds_read_b128 v[132:135], v35 offset:30720
	v_lshl_add_u64 v[80:81], v[16:17], 0, s[42:43]
	v_lshl_add_u64 v[16:17], v[80:81], 0, v[8:9]
	s_waitcnt lgkmcnt(0)
	v_mfma_f32_16x16x32_bf16 v[52:55], v[108:111], v[92:95], v[52:55]
	v_lshl_add_u32 v146, v83, 13, v39
	v_ashrrev_i32_e32 v147, 31, v146
	v_lshl_add_u64 v[164:165], v[80:81], 0, v[162:163]
	v_mfma_f32_16x16x32_bf16 v[60:63], v[140:143], v[92:95], v[60:63]
	v_lshl_add_u64 v[168:169], v[80:81], 0, v[166:167]
	v_or_b32_e32 v39, 16, v39
	v_mfma_f32_16x16x32_bf16 v[68:71], v[112:115], v[92:95], v[68:71]
	v_mfma_f32_16x16x32_bf16 v[76:79], v[116:119], v[92:95], v[76:79]
	v_mfma_f32_16x16x32_bf16 v[88:91], v[120:123], v[92:95], v[88:91]
	v_mfma_f32_16x16x32_bf16 v[96:99], v[124:127], v[92:95], v[96:99]
	v_mfma_f32_16x16x32_bf16 v[104:107], v[128:131], v[92:95], v[104:107]
	v_mfma_f32_16x16x32_bf16 v[44:47], v[132:135], v[92:95], v[44:47]
	v_mfma_f32_16x16x32_bf16 v[4:7], v[108:111], v[100:103], v[4:7]
	v_mfma_f32_16x16x32_bf16 v[40:43], v[140:143], v[100:103], v[40:43]
	v_mfma_f32_16x16x32_bf16 v[56:59], v[112:115], v[100:103], v[56:59]
	v_mfma_f32_16x16x32_bf16 v[64:67], v[116:119], v[100:103], v[64:67]
	v_mfma_f32_16x16x32_bf16 v[72:75], v[120:123], v[100:103], v[72:75]
	v_mfma_f32_16x16x32_bf16 v[84:87], v[124:127], v[100:103], v[84:87]
	v_mfma_f32_16x16x32_bf16 v[92:95], v[128:131], v[100:103], v[0:3]
	s_nop 2
	ds_read_b128 v[0:3], v37 offset:16384
	ds_read_b128 v[108:111], v37 offset:18432
	v_mfma_f32_16x16x32_bf16 v[48:51], v[132:135], v[100:103], v[48:51]
	ds_read_b128 v[100:103], v36
	ds_read_b128 v[112:115], v36 offset:2048
	ds_read_b128 v[116:119], v37 offset:20480
	ds_read_b128 v[120:123], v37 offset:22528
	ds_read_b128 v[124:127], v37 offset:24576
	ds_read_b128 v[128:131], v37 offset:26624
	ds_read_b128 v[132:135], v37 offset:28672
	ds_read_b128 v[136:139], v37 offset:30720
	s_waitcnt vmcnt(0) lgkmcnt(0)
	s_barrier
	global_load_dwordx4 v[172:175], v[16:17], off
	global_load_dwordx4 v[176:179], v[16:17], off offset:16
	global_load_dwordx4 v[180:183], v[16:17], off offset:128
	global_load_dwordx4 v[184:187], v[16:17], off offset:144
	global_load_dwordx4 v[188:191], v[16:17], off offset:256
	global_load_dwordx4 v[192:195], v[16:17], off offset:272
	global_load_dwordx4 v[196:199], v[16:17], off offset:384
	global_load_dwordx4 v[200:203], v[16:17], off offset:400
	v_mul_hi_i32 v236, v39, s45
	v_lshrrev_b32_e32 v237, 31, v236
	v_ashrrev_i32_e32 v236, 11, v236
	v_add_u32_e32 v236, v236, v237
	v_mad_i32_i24 v237, v236, s46, v39
	v_cmp_lt_i32_e64 s[52:53], s47, v237
	v_cndmask_b32_e64 v236, 2, v236, s[52:53]
	v_mul_hi_i32_i24_e32 v237, 0x6000, v236
	v_mul_i32_i24_e32 v236, 0x6000, v236
	v_lshl_add_u64 v[238:239], s[94:95], 0, v[236:237]
	v_lshl_add_u64 v[238:239], v[238:239], 0, s[42:43]
	v_lshl_add_u64 v[238:239], v[238:239], 0, v[8:9]
	global_load_dwordx4 v[204:207], v[238:239], off
	global_load_dwordx4 v[208:211], v[238:239], off offset:16
	global_load_dwordx4 v[212:215], v[238:239], off offset:128
	global_load_dwordx4 v[216:219], v[238:239], off offset:144
	global_load_dwordx4 v[220:223], v[238:239], off offset:256
	global_load_dwordx4 v[224:227], v[238:239], off offset:272
	global_load_dwordx4 v[228:231], v[238:239], off offset:384
	global_load_dwordx4 v[232:235], v[238:239], off offset:400
	v_mfma_f32_16x16x32_bf16 v[60:63], v[108:111], v[100:103], v[60:63]
	v_mov_b32_e32 v17, v9
	v_or_b32_e32 v16, 16, v8
	v_lshl_add_u64 v[160:161], v[80:81], 0, v[16:17]
	v_mfma_f32_16x16x32_bf16 v[68:71], v[116:119], v[100:103], v[68:71]
	v_mfma_f32_16x16x32_bf16 v[40:43], v[108:111], v[112:115], v[40:43]
	v_mfma_f32_16x16x32_bf16 v[56:59], v[116:119], v[112:115], v[56:59]
	ds_read_b128 v[108:111], v35 offset:49152
	ds_read_b128 v[116:119], v34 offset:32768
	v_mfma_f32_16x16x32_bf16 v[52:55], v[0:3], v[100:103], v[52:55]
	v_mfma_f32_16x16x32_bf16 v[76:79], v[120:123], v[100:103], v[76:79]
	v_mfma_f32_16x16x32_bf16 v[88:91], v[124:127], v[100:103], v[88:91]
	v_mfma_f32_16x16x32_bf16 v[96:99], v[128:131], v[100:103], v[96:99]
	v_mfma_f32_16x16x32_bf16 v[104:107], v[132:135], v[100:103], v[104:107]
	v_mfma_f32_16x16x32_bf16 v[44:47], v[136:139], v[100:103], v[44:47]
	v_mfma_f32_16x16x32_bf16 v[100:103], v[0:3], v[112:115], v[4:7]
	v_lshl_add_u64 v[0:1], v[146:147], 0, s[8:9]
	v_lshlrev_b64 v[0:1], 12, v[0:1]
	v_lshl_add_u64 v[0:1], s[6:7], 0, v[0:1]
	s_waitcnt lgkmcnt(0)
	v_mfma_f32_16x16x32_bf16 v[52:55], v[108:111], v[116:119], v[52:55]
	v_lshl_add_u64 v[158:159], v[0:1], 0, v[8:9]
	v_mfma_f32_16x16x32_bf16 v[64:67], v[120:123], v[112:115], v[64:67]
	ds_read_b128 v[120:123], v37 offset:49152
	ds_read_b128 v[4:7], v34 offset:34816
	ds_read_b128 v[146:149], v35 offset:51200
	ds_read_b128 v[150:153], v36 offset:32768
	ds_read_b128 v[0:3], v36 offset:34816
	ds_read_b128 v[154:157], v37 offset:51200
	s_waitcnt lgkmcnt(2)
	v_mfma_f32_16x16x32_bf16 v[52:55], v[120:123], v[150:153], v[52:55]
	v_mfma_f32_16x16x32_bf16 v[60:63], v[146:149], v[116:119], v[60:63]
	s_waitcnt vmcnt(15)
	s_nop 5
	v_pk_mul_f32 v[54:55], v[54:55], v[174:175]
	v_pk_mul_f32 v[52:53], v[52:53], v[172:173]
	global_store_dwordx4 v[158:159], v[52:55], off
	s_waitcnt lgkmcnt(0)
	v_mfma_f32_16x16x32_bf16 v[60:63], v[154:157], v[150:153], v[60:63]
	v_mov_b32_e32 v161, v9
	v_or_b32_e32 v160, 0x80, v8
	v_lshl_add_u64 v[140:141], v[80:81], 0, v[160:161]
	v_mfma_f32_16x16x32_bf16 v[48:51], v[136:139], v[112:115], v[48:51]
	v_mfma_f32_16x16x32_bf16 v[40:43], v[146:149], v[4:7], v[40:43]
	s_waitcnt vmcnt(15)
	s_nop 1
	v_pk_mul_f32 v[178:179], v[62:63], v[178:179]
	v_pk_mul_f32 v[176:177], v[60:61], v[176:177]
	global_store_dwordx4 v[158:159], v[176:179], off offset:16
	v_mfma_f32_16x16x32_bf16 v[60:63], v[124:127], v[112:115], v[72:75]
	v_mfma_f32_16x16x32_bf16 v[72:75], v[128:131], v[112:115], v[84:87]
	s_nop 2
	ds_read_b128 v[84:87], v35 offset:53248
	ds_read_b128 v[124:127], v35 offset:55296
	ds_read_b128 v[128:131], v37 offset:53248
	ds_read_b128 v[140:143], v37 offset:55296
	s_waitcnt lgkmcnt(3)
	v_mfma_f32_16x16x32_bf16 v[68:71], v[84:87], v[116:119], v[68:71]
	s_waitcnt lgkmcnt(1)
	v_mfma_f32_16x16x32_bf16 v[68:71], v[128:131], v[150:153], v[68:71]
	v_mfma_f32_16x16x32_bf16 v[40:43], v[154:157], v[0:3], v[40:43]
	v_mfma_f32_16x16x32_bf16 v[56:59], v[84:87], v[4:7], v[56:59]
	s_waitcnt vmcnt(15)
	s_nop 4
	v_pk_mul_f32 v[182:183], v[70:71], v[182:183]
	v_pk_mul_f32 v[180:181], v[68:69], v[180:181]
	global_store_dwordx4 v[158:159], v[180:183], off offset:128
	v_mfma_f32_16x16x32_bf16 v[68:71], v[124:127], v[116:119], v[76:79]
	v_mov_b32_e32 v165, v9
	v_or_b32_e32 v164, 0x100, v8
	s_waitcnt lgkmcnt(0)
	v_mfma_f32_16x16x32_bf16 v[68:71], v[140:143], v[150:153], v[68:71]
	v_lshl_add_u64 v[76:77], v[80:81], 0, v[164:165]
	v_mfma_f32_16x16x32_bf16 v[56:59], v[128:131], v[0:3], v[56:59]
	v_mfma_f32_16x16x32_bf16 v[64:67], v[124:127], v[4:7], v[64:67]
	s_waitcnt vmcnt(15)
	s_nop 3
	v_pk_mul_f32 v[186:187], v[70:71], v[186:187]
	v_pk_mul_f32 v[184:185], v[68:69], v[184:185]
	global_store_dwordx4 v[158:159], v[184:187], off offset:144
	v_mfma_f32_16x16x32_bf16 v[68:71], v[132:135], v[112:115], v[92:95]
	ds_read_b128 v[76:79], v35 offset:57344
	s_nop 1
	ds_read_b128 v[92:95], v35 offset:59392
	ds_read_b128 v[112:115], v37 offset:57344
	ds_read_b128 v[132:135], v37 offset:59392
	s_waitcnt lgkmcnt(3)
	v_mfma_f32_16x16x32_bf16 v[88:91], v[76:79], v[116:119], v[88:91]
	s_waitcnt lgkmcnt(1)
	v_mfma_f32_16x16x32_bf16 v[88:91], v[112:115], v[150:153], v[88:91]
	v_mfma_f32_16x16x32_bf16 v[60:63], v[76:79], v[4:7], v[60:63]
	s_waitcnt vmcnt(15)
	s_nop 5
	v_pk_mul_f32 v[190:191], v[90:91], v[190:191]
	v_pk_mul_f32 v[188:189], v[88:89], v[188:189]
	global_store_dwordx4 v[158:159], v[188:191], off offset:256
	v_mfma_f32_16x16x32_bf16 v[88:91], v[92:95], v[116:119], v[96:99]
	v_mov_b32_e32 v169, v9
	v_or_b32_e32 v168, 0x180, v8
	s_nop 0
	ds_read_b128 v[96:99], v35 offset:61440
	ds_read_b128 v[136:139], v35 offset:63488
	s_waitcnt lgkmcnt(2)
	v_mfma_f32_16x16x32_bf16 v[88:91], v[132:135], v[150:153], v[88:91]
	v_lshl_add_u64 v[170:171], v[80:81], 0, v[168:169]
	s_waitcnt lgkmcnt(1)
	v_mfma_f32_16x16x32_bf16 v[104:107], v[96:99], v[116:119], v[104:107]
	s_waitcnt lgkmcnt(0)
	v_mfma_f32_16x16x32_bf16 v[44:47], v[136:139], v[116:119], v[44:47]
	v_mov_b32_e32 v117, v9
	v_or_b32_e32 v116, 0x190, v8
	v_lshl_add_u64 v[80:81], v[80:81], 0, v[116:117]
	v_mfma_f32_16x16x32_bf16 v[68:71], v[96:99], v[4:7], v[68:71]
	s_waitcnt vmcnt(15)
	v_pk_mul_f32 v[194:195], v[90:91], v[194:195]
	v_pk_mul_f32 v[192:193], v[88:89], v[192:193]
	global_store_dwordx4 v[158:159], v[192:195], off offset:272
	v_mfma_f32_16x16x32_bf16 v[88:91], v[108:111], v[4:7], v[100:103]
	s_nop 2
	ds_read_b128 v[100:103], v37 offset:61440
	ds_read_b128 v[108:111], v37 offset:63488
	s_waitcnt lgkmcnt(1)
	v_mfma_f32_16x16x32_bf16 v[104:107], v[100:103], v[150:153], v[104:107]
	s_waitcnt lgkmcnt(0)
	v_mfma_f32_16x16x32_bf16 v[44:47], v[108:111], v[150:153], v[44:47]
	s_waitcnt vmcnt(15)
	s_nop 4
	v_pk_mul_f32 v[198:199], v[106:107], v[198:199]
	v_pk_mul_f32 v[196:197], v[104:105], v[196:197]
	global_store_dwordx4 v[158:159], v[196:199], off offset:384
	v_mul_hi_i32 v80, v39, s45
	v_lshrrev_b32_e32 v81, 31, v80
	v_ashrrev_i32_e32 v80, 11, v80
	v_add_u32_e32 v80, v80, v81
	v_mad_i32_i24 v81, v80, s46, v39
	v_cmp_lt_i32_e32 vcc, s47, v81
	s_waitcnt vmcnt(15)
	v_pk_mul_f32 v[46:47], v[46:47], v[202:203]
	v_cndmask_b32_e32 v80, 2, v80, vcc
	v_mul_hi_i32_i24_e32 v81, 0x6000, v80
	v_mul_i32_i24_e32 v80, 0x6000, v80
	v_lshl_add_u64 v[76:77], s[94:95], 0, v[80:81]
	v_lshl_add_u64 v[76:77], v[76:77], 0, s[42:43]
	v_pk_mul_f32 v[44:45], v[44:45], v[200:201]
	v_lshl_add_u64 v[78:79], v[76:77], 0, v[8:9]
	global_store_dwordx4 v[158:159], v[44:47], off offset:400
	v_mul_hi_i32 v78, v39, s44
	v_lshrrev_b32_e32 v79, 31, v78
	v_mfma_f32_16x16x32_bf16 v[52:55], v[92:95], v[4:7], v[72:75]
	v_lshl_add_u64 v[16:17], v[76:77], 0, v[16:17]
	s_nop 1
	v_lshrrev_b32_e32 v72, 11, v78
	v_add_u32_e32 v72, v72, v79
	v_lshl_add_u32 v72, v72, 13, v39
	v_ashrrev_i32_e32 v73, 31, v72
	v_lshl_add_u64 v[72:73], v[72:73], 0, s[8:9]
	v_lshlrev_b64 v[78:79], 12, v[72:73]
	v_mfma_f32_16x16x32_bf16 v[72:75], v[120:123], v[0:3], v[88:91]
	v_lshl_add_u64 v[78:79], s[6:7], 0, v[78:79]
	v_lshl_add_u64 v[78:79], v[78:79], 0, v[8:9]
	v_mfma_f32_16x16x32_bf16 v[4:7], v[136:139], v[4:7], v[48:51]
	s_waitcnt vmcnt(15)
	s_nop 3
	v_pk_mul_f32 v[206:207], v[74:75], v[206:207]
	v_pk_mul_f32 v[204:205], v[72:73], v[204:205]
	global_store_dwordx4 v[78:79], v[204:207], off
	v_lshl_add_u64 v[16:17], v[76:77], 0, v[160:161]
	s_waitcnt vmcnt(15)
	v_pk_mul_f32 v[42:43], v[42:43], v[210:211]
	v_pk_mul_f32 v[40:41], v[40:41], v[208:209]
	global_store_dwordx4 v[78:79], v[40:43], off offset:16
	v_lshl_add_u64 v[16:17], v[76:77], 0, v[162:163]
	v_mfma_f32_16x16x32_bf16 v[44:47], v[140:143], v[0:3], v[64:67]
	s_waitcnt vmcnt(15)
	v_pk_mul_f32 v[214:215], v[58:59], v[214:215]
	v_pk_mul_f32 v[212:213], v[56:57], v[212:213]
	global_store_dwordx4 v[78:79], v[212:215], off offset:128
	v_lshl_add_u64 v[16:17], v[76:77], 0, v[164:165]
	v_mfma_f32_16x16x32_bf16 v[56:59], v[112:115], v[0:3], v[60:63]
	s_waitcnt vmcnt(15)
	v_pk_mul_f32 v[218:219], v[46:47], v[218:219]
	v_pk_mul_f32 v[216:217], v[44:45], v[216:217]
	global_store_dwordx4 v[78:79], v[216:219], off offset:144
	v_lshl_add_u64 v[16:17], v[76:77], 0, v[166:167]
	v_mfma_f32_16x16x32_bf16 v[44:47], v[132:135], v[0:3], v[52:55]
	s_waitcnt vmcnt(15)
	v_pk_mul_f32 v[222:223], v[58:59], v[222:223]
	v_pk_mul_f32 v[220:221], v[56:57], v[220:221]
	global_store_dwordx4 v[78:79], v[220:223], off offset:256
	v_lshl_add_u64 v[16:17], v[76:77], 0, v[168:169]
	v_mfma_f32_16x16x32_bf16 v[52:55], v[100:103], v[0:3], v[68:71]
	s_waitcnt vmcnt(15)
	v_pk_mul_f32 v[226:227], v[46:47], v[226:227]
	v_pk_mul_f32 v[224:225], v[44:45], v[224:225]
	global_store_dwordx4 v[78:79], v[224:227], off offset:272
	v_lshl_add_u64 v[16:17], v[76:77], 0, v[116:117]
	v_mfma_f32_16x16x32_bf16 v[0:3], v[108:111], v[0:3], v[4:7]
	s_waitcnt vmcnt(15)
	v_pk_mul_f32 v[230:231], v[54:55], v[230:231]
	v_pk_mul_f32 v[228:229], v[52:53], v[228:229]
	global_store_dwordx4 v[78:79], v[228:231], off offset:384
	s_waitcnt vmcnt(15)
	s_nop 1
	v_pk_mul_f32 v[2:3], v[2:3], v[234:235]
	v_pk_mul_f32 v[0:1], v[0:1], v[232:233]
	global_store_dwordx4 v[78:79], v[0:3], off offset:400
	s_cbranch_scc1 .LBB0_874

.LBB0_1091:
	s_add_i32 s48, s47, 0x8000
	s_and_b32 s8, s47, 0x8000
	s_and_b32 s47, s48, 0x8000
	s_add_i32 s49, s8, 0
	s_add_i32 s8, s47, 0
	s_add_u32 s71, s8, s75
	s_mov_b32 m0, s71
	s_waitcnt vmcnt(0) lgkmcnt(0)
	s_barrier
	global_load_lds_dwordx4 v236, s[84:85]
	s_add_u32 m0, s71, 0x4000
	s_nop 0
	global_load_lds_dwordx4 v237, s[72:73]
	s_add_u32 m0, s71, 0x1000
	s_nop 0
	global_load_lds_dwordx4 v238, s[84:85]
	s_add_u32 m0, s71, 0x5000
	s_nop 0
	global_load_lds_dwordx4 v239, s[72:73]
	s_add_u32 m0, s71, 0x2000
	s_nop 0
	global_load_lds_dwordx4 v240, s[84:85]
	s_add_u32 m0, s71, 0x6000
	s_nop 0
	global_load_lds_dwordx4 v241, s[72:73]
	s_add_u32 m0, s71, 0x3000
	s_nop 0
	global_load_lds_dwordx4 v242, s[84:85]
	s_add_u32 m0, s71, 0x7000
	s_nop 0
	global_load_lds_dwordx4 v243, s[72:73]
	s_add_u32 s84, s84, 0x80
	s_addc_u32 s85, s85, 0
	s_add_u32 s72, s72, 0x80
	s_addc_u32 s73, s73, 0
	v_add3_u32 v169, s49, v84, v87
	v_add3_u32 v210, s49, v87, v89
	v_add3_u32 v211, s49, v84, v90
	v_add3_u32 v212, s49, v89, v90
	ds_read_b128 v[104:107], v210
	ds_read_b128 v[68:71], v169 offset:16384
	ds_read_b128 v[100:103], v169 offset:18432
	ds_read_b128 v[108:111], v210 offset:2048
	ds_read_b128 v[112:115], v169 offset:20480
	ds_read_b128 v[116:119], v169 offset:22528
	ds_read_b128 v[120:123], v169 offset:24576
	ds_read_b128 v[124:127], v169 offset:26624
	ds_read_b128 v[128:131], v169 offset:28672
	ds_read_b128 v[132:135], v169 offset:30720
	ds_read_b128 v[178:181], v212
	ds_read_b128 v[170:173], v211 offset:16384
	ds_read_b128 v[174:177], v211 offset:18432
	ds_read_b128 v[182:185], v212 offset:2048
	ds_read_b128 v[186:189], v211 offset:20480
	ds_read_b128 v[190:193], v211 offset:22528
	ds_read_b128 v[194:197], v211 offset:24576
	ds_read_b128 v[198:201], v211 offset:26624
	ds_read_b128 v[202:205], v211 offset:28672
	ds_read_b128 v[206:209], v211 offset:30720
	s_add_u32 s36, s36, 0x80
	s_addc_u32 s37, s37, 0
	s_cmpk_eq_i32 s36, 0x780
	s_mov_b32 s47, s48
	s_waitcnt lgkmcnt(15)
	v_mfma_f32_16x16x32_bf16 v[60:63], v[68:71], v[104:107], v[60:63]
	v_mfma_f32_16x16x32_bf16 v[56:59], v[100:103], v[104:107], v[56:59]
	v_mfma_f32_16x16x32_bf16 v[28:31], v[68:71], v[108:111], v[28:31]
	v_mfma_f32_16x16x32_bf16 v[24:27], v[100:103], v[108:111], v[24:27]
	v_mfma_f32_16x16x32_bf16 v[52:55], v[112:115], v[104:107], v[52:55]
	v_mfma_f32_16x16x32_bf16 v[16:19], v[112:115], v[108:111], v[16:19]
	s_waitcnt lgkmcnt(14)
	v_mfma_f32_16x16x32_bf16 v[48:51], v[116:119], v[104:107], v[48:51]
	v_mfma_f32_16x16x32_bf16 v[12:15], v[116:119], v[108:111], v[12:15]
	s_waitcnt lgkmcnt(13)
	v_mfma_f32_16x16x32_bf16 v[44:47], v[120:123], v[104:107], v[44:47]
	v_mfma_f32_16x16x32_bf16 v[8:11], v[120:123], v[108:111], v[8:11]
	s_waitcnt lgkmcnt(12)
	v_mfma_f32_16x16x32_bf16 v[40:43], v[124:127], v[104:107], v[40:43]
	v_mfma_f32_16x16x32_bf16 v[4:7], v[124:127], v[108:111], v[4:7]
	s_waitcnt lgkmcnt(11)
	v_mfma_f32_16x16x32_bf16 v[36:39], v[128:131], v[104:107], v[36:39]
	v_mfma_f32_16x16x32_bf16 v[0:3], v[128:131], v[108:111], v[0:3]
	s_waitcnt lgkmcnt(10)
	v_mfma_f32_16x16x32_bf16 v[32:35], v[132:135], v[104:107], v[32:35]
	v_mfma_f32_16x16x32_bf16 v[20:23], v[132:135], v[108:111], v[20:23]
	s_waitcnt lgkmcnt(8)
	v_mfma_f32_16x16x32_bf16 v[60:63], v[170:173], v[178:181], v[60:63]
	s_waitcnt lgkmcnt(7)
	v_mfma_f32_16x16x32_bf16 v[56:59], v[174:177], v[178:181], v[56:59]
	s_waitcnt lgkmcnt(6)
	v_mfma_f32_16x16x32_bf16 v[28:31], v[170:173], v[182:185], v[28:31]
	v_mfma_f32_16x16x32_bf16 v[24:27], v[174:177], v[182:185], v[24:27]
	s_waitcnt lgkmcnt(5)
	v_mfma_f32_16x16x32_bf16 v[52:55], v[186:189], v[178:181], v[52:55]
	v_mfma_f32_16x16x32_bf16 v[16:19], v[186:189], v[182:185], v[16:19]
	s_waitcnt lgkmcnt(4)
	v_mfma_f32_16x16x32_bf16 v[48:51], v[190:193], v[178:181], v[48:51]
	v_mfma_f32_16x16x32_bf16 v[12:15], v[190:193], v[182:185], v[12:15]
	s_waitcnt lgkmcnt(3)
	v_mfma_f32_16x16x32_bf16 v[44:47], v[194:197], v[178:181], v[44:47]
	v_mfma_f32_16x16x32_bf16 v[8:11], v[194:197], v[182:185], v[8:11]
	s_waitcnt lgkmcnt(2)
	v_mfma_f32_16x16x32_bf16 v[40:43], v[198:201], v[178:181], v[40:43]
	v_mfma_f32_16x16x32_bf16 v[4:7], v[198:201], v[182:185], v[4:7]
	s_waitcnt lgkmcnt(1)
	v_mfma_f32_16x16x32_bf16 v[36:39], v[202:205], v[178:181], v[36:39]
	v_mfma_f32_16x16x32_bf16 v[0:3], v[202:205], v[182:185], v[0:3]
	s_waitcnt lgkmcnt(0)
	v_mfma_f32_16x16x32_bf16 v[32:35], v[206:209], v[178:181], v[32:35]
	v_mfma_f32_16x16x32_bf16 v[20:23], v[206:209], v[182:185], v[20:23]
	s_cbranch_scc0 .LBB0_1091
	v_lshl_add_u32 v99, s46, 7, v85
	v_mul_hi_i32 v64, v99, s39
	v_lshrrev_b32_e32 v65, 31, v64
	v_ashrrev_i32_e32 v64, 11, v64
	v_add_u32_e32 v64, v64, v65
	v_mad_i32_i24 v65, v64, s40, v99
	v_cmp_lt_i32_e32 vcc, s41, v65
	v_lshl_or_b32 v72, s45, 9, v86
	s_waitcnt vmcnt(0)
	v_cndmask_b32_e32 v64, 2, v64, vcc
	v_mul_hi_i32_i24_e32 v65, 0x6000, v64
	v_mul_i32_i24_e32 v64, 0x6000, v64
	v_lshl_add_u64 v[64:65], s[94:95], 0, v[64:65]
	v_lshl_add_u64 v[150:151], v[64:65], 0, s[34:35]
	v_lshl_add_u64 v[64:65], v[150:151], 0, v[72:73]
	s_barrier
	global_load_dwordx4 v[172:175], v[64:65], off
	global_load_dwordx4 v[176:179], v[64:65], off offset:16
	global_load_dwordx4 v[180:183], v[64:65], off offset:128
	global_load_dwordx4 v[184:187], v[64:65], off offset:144
	global_load_dwordx4 v[188:191], v[64:65], off offset:256
	global_load_dwordx4 v[192:195], v[64:65], off offset:272
	global_load_dwordx4 v[196:199], v[64:65], off offset:384
	global_load_dwordx4 v[200:203], v[64:65], off offset:400
	v_or_b32_e32 v238, 16, v99
	v_mul_hi_i32 v236, v238, s39
	v_lshrrev_b32_e32 v237, 31, v236
	v_ashrrev_i32_e32 v236, 11, v236
	v_add_u32_e32 v236, v236, v237
	v_mad_i32_i24 v237, v236, s40, v238
	v_cmp_lt_i32_e64 s[52:53], s41, v237
	v_cndmask_b32_e64 v236, 2, v236, s[52:53]
	v_mul_hi_i32_i24_e32 v237, 0x6000, v236
	v_mul_i32_i24_e32 v236, 0x6000, v236
	v_lshl_add_u64 v[238:239], s[94:95], 0, v[236:237]
	v_lshl_add_u64 v[238:239], v[238:239], 0, s[34:35]
	v_lshl_add_u64 v[238:239], v[238:239], 0, v[72:73]
	global_load_dwordx4 v[204:207], v[238:239], off
	global_load_dwordx4 v[208:211], v[238:239], off offset:16
	global_load_dwordx4 v[212:215], v[238:239], off offset:128
	global_load_dwordx4 v[216:219], v[238:239], off offset:144
	global_load_dwordx4 v[220:223], v[238:239], off offset:256
	global_load_dwordx4 v[224:227], v[238:239], off offset:272
	global_load_dwordx4 v[228:231], v[238:239], off offset:384
	global_load_dwordx4 v[232:235], v[238:239], off offset:400
	v_add3_u32 v64, s8, v87, v89
	v_add_u32_e32 v68, s8, v84
	ds_read_b128 v[104:107], v64
	ds_read_b128 v[108:111], v64 offset:2048
	v_add3_u32 v65, s8, v90, v89
	v_add_u32_e32 v145, v68, v87
	ds_read_b128 v[112:115], v65
	ds_read_b128 v[64:67], v65 offset:2048
	v_add_u32_e32 v168, v68, v90
	ds_read_b128 v[116:119], v145 offset:16384
	ds_read_b128 v[120:123], v145 offset:18432
	ds_read_b128 v[124:127], v168 offset:16384
	ds_read_b128 v[68:71], v168 offset:18432
	v_mul_hi_i32 v128, v99, s38
	s_waitcnt lgkmcnt(3)
	v_mfma_f32_16x16x32_bf16 v[60:63], v[116:119], v[104:107], v[60:63]
	v_lshrrev_b32_e32 v129, 31, v128
	v_lshrrev_b32_e32 v128, 11, v128
	v_add_u32_e32 v128, v128, v129
	v_lshl_add_u32 v128, v128, 13, v99
	s_lshl_b32 s8, s44, 9
	v_ashrrev_i32_e32 v129, 31, v128
	s_waitcnt lgkmcnt(1)
	v_mfma_f32_16x16x32_bf16 v[60:63], v[124:127], v[112:115], v[60:63]
	v_lshl_add_u64 v[128:129], v[128:129], 0, s[8:9]
	v_lshlrev_b64 v[128:129], 12, v[128:129]
	v_lshl_add_u64 v[128:129], s[6:7], 0, v[128:129]
	v_mov_b32_e32 v153, v73
	v_or_b32_e32 v152, 16, v72
	v_lshl_add_u64 v[154:155], v[128:129], 0, v[72:73]
	v_lshl_add_u64 v[128:129], v[150:151], 0, v[152:153]
	v_mfma_f32_16x16x32_bf16 v[56:59], v[120:123], v[104:107], v[56:59]
	v_mov_b32_e32 v157, v73
	v_or_b32_e32 v156, 0x80, v72
	v_mov_b32_e32 v159, v73
	s_waitcnt lgkmcnt(0)
	v_mfma_f32_16x16x32_bf16 v[56:59], v[68:71], v[112:115], v[56:59]
	v_or_b32_e32 v158, 0x90, v72
	v_lshl_add_u64 v[136:137], v[150:151], 0, v[158:159]
	v_mov_b32_e32 v161, v73
	v_or_b32_e32 v160, 0x100, v72
	v_mov_b32_e32 v163, v73
	v_or_b32_e32 v162, 0x110, v72
	v_lshl_add_u64 v[146:147], v[150:151], 0, v[162:163]
	v_mov_b32_e32 v165, v73
	v_or_b32_e32 v164, 0x180, v72
	v_lshl_add_u64 v[166:167], v[150:151], 0, v[164:165]
	v_mfma_f32_16x16x32_bf16 v[28:31], v[116:119], v[108:111], v[28:31]
	v_or_b32_e32 v99, 16, v99
	s_add_i32 s43, s43, s33
	s_add_i32 s42, s42, s33
	v_mfma_f32_16x16x32_bf16 v[28:31], v[124:127], v[64:67], v[28:31]
	s_cmpk_gt_i32 s43, 0x7f
	s_waitcnt vmcnt(15)
	v_pk_mul_f32 v[62:63], v[62:63], v[174:175]
	v_pk_mul_f32 v[60:61], v[60:61], v[172:173]
	global_store_dwordx4 v[154:155], v[60:63], off
	v_lshl_add_u64 v[100:101], v[150:151], 0, v[156:157]
	v_mfma_f32_16x16x32_bf16 v[24:27], v[120:123], v[108:111], v[24:27]
	s_waitcnt vmcnt(15)
	v_pk_mul_f32 v[58:59], v[58:59], v[178:179]
	v_pk_mul_f32 v[56:57], v[56:57], v[176:177]
	global_store_dwordx4 v[154:155], v[56:59], off offset:16
	ds_read_b128 v[60:63], v145 offset:20480
	ds_read_b128 v[100:103], v168 offset:20480
	s_waitcnt lgkmcnt(1)
	v_mfma_f32_16x16x32_bf16 v[52:55], v[60:63], v[104:107], v[52:55]
	ds_read_b128 v[128:131], v145 offset:22528
	ds_read_b128 v[132:135], v168 offset:22528
	s_waitcnt lgkmcnt(2)
	v_mfma_f32_16x16x32_bf16 v[52:55], v[100:103], v[112:115], v[52:55]
	s_waitcnt lgkmcnt(1)
	v_mfma_f32_16x16x32_bf16 v[48:51], v[128:131], v[104:107], v[48:51]
	s_waitcnt vmcnt(15)
	s_nop 4
	v_pk_mul_f32 v[54:55], v[54:55], v[182:183]
	v_pk_mul_f32 v[52:53], v[52:53], v[180:181]
	global_store_dwordx4 v[154:155], v[52:55], off offset:128
	s_waitcnt lgkmcnt(0)
	v_mfma_f32_16x16x32_bf16 v[48:51], v[132:135], v[112:115], v[48:51]
	v_lshl_add_u64 v[56:57], v[150:151], 0, v[160:161]
	v_mfma_f32_16x16x32_bf16 v[24:27], v[68:71], v[64:67], v[24:27]
	v_mfma_f32_16x16x32_bf16 v[16:19], v[60:63], v[108:111], v[16:19]
	s_waitcnt vmcnt(15)
	s_nop 3
	v_pk_mul_f32 v[50:51], v[50:51], v[186:187]
	v_pk_mul_f32 v[48:49], v[48:49], v[184:185]
	global_store_dwordx4 v[154:155], v[48:51], off offset:144
	ds_read_b128 v[52:55], v145 offset:24576
	ds_read_b128 v[56:59], v168 offset:24576
	s_waitcnt lgkmcnt(1)
	v_mfma_f32_16x16x32_bf16 v[44:47], v[52:55], v[104:107], v[44:47]
	ds_read_b128 v[136:139], v145 offset:26624
	ds_read_b128 v[140:143], v168 offset:26624
	s_waitcnt lgkmcnt(2)
	v_mfma_f32_16x16x32_bf16 v[44:47], v[56:59], v[112:115], v[44:47]
	s_waitcnt lgkmcnt(1)
	v_mfma_f32_16x16x32_bf16 v[40:43], v[136:139], v[104:107], v[40:43]
	s_waitcnt vmcnt(15)
	s_nop 4
	v_pk_mul_f32 v[46:47], v[46:47], v[190:191]
	v_pk_mul_f32 v[44:45], v[44:45], v[188:189]
	global_store_dwordx4 v[154:155], v[44:47], off offset:256
	s_waitcnt lgkmcnt(0)
	v_mfma_f32_16x16x32_bf16 v[40:43], v[140:143], v[112:115], v[40:43]
	ds_read_b128 v[48:51], v145 offset:28672
	ds_read_b128 v[146:149], v145 offset:30720
	s_waitcnt lgkmcnt(1)
	v_mfma_f32_16x16x32_bf16 v[36:39], v[48:51], v[104:107], v[36:39]
	s_waitcnt vmcnt(15)
	s_nop 2
	v_pk_mul_f32 v[42:43], v[42:43], v[194:195]
	v_pk_mul_f32 v[40:41], v[40:41], v[192:193]
	global_store_dwordx4 v[154:155], v[40:43], off offset:272
	ds_read_b128 v[44:47], v168 offset:28672
	s_waitcnt lgkmcnt(1)
	v_mfma_f32_16x16x32_bf16 v[32:35], v[146:149], v[104:107], v[32:35]
	ds_read_b128 v[104:107], v168 offset:30720
	v_mov_b32_e32 v167, v73
	v_or_b32_e32 v166, 0x190, v72
	s_waitcnt lgkmcnt(1)
	v_mfma_f32_16x16x32_bf16 v[36:39], v[44:47], v[112:115], v[36:39]
	v_lshl_add_u64 v[116:117], v[150:151], 0, v[166:167]
	s_waitcnt vmcnt(15)
	s_nop 5
	v_pk_mul_f32 v[38:39], v[38:39], v[198:199]
	v_pk_mul_f32 v[36:37], v[36:37], v[196:197]
	global_store_dwordx4 v[154:155], v[36:39], off offset:384
	v_mul_hi_i32 v40, v99, s39
	v_lshrrev_b32_e32 v41, 31, v40
	v_ashrrev_i32_e32 v40, 11, v40
	v_add_u32_e32 v40, v40, v41
	v_mad_i32_i24 v41, v40, s40, v99
	v_cmp_lt_i32_e32 vcc, s41, v41
	s_waitcnt lgkmcnt(0)
	v_mfma_f32_16x16x32_bf16 v[32:35], v[104:107], v[112:115], v[32:35]
	v_cndmask_b32_e32 v40, 2, v40, vcc
	v_mul_hi_i32_i24_e32 v41, 0x6000, v40
	v_mul_i32_i24_e32 v40, 0x6000, v40
	v_lshl_add_u64 v[40:41], s[94:95], 0, v[40:41]
	v_lshl_add_u64 v[40:41], v[40:41], 0, s[34:35]
	v_lshl_add_u64 v[42:43], v[40:41], 0, v[72:73]
	v_mfma_f32_16x16x32_bf16 v[16:19], v[100:103], v[64:67], v[16:19]
	s_waitcnt vmcnt(15)
	v_pk_mul_f32 v[34:35], v[34:35], v[202:203]
	v_pk_mul_f32 v[32:33], v[32:33], v[200:201]
	global_store_dwordx4 v[154:155], v[32:35], off offset:400
	v_mul_hi_i32 v36, v99, s38
	v_lshrrev_b32_e32 v37, 31, v36
	v_lshrrev_b32_e32 v36, 11, v36
	v_add_u32_e32 v36, v36, v37
	v_lshl_add_u32 v36, v36, 13, v99
	v_ashrrev_i32_e32 v37, 31, v36
	v_lshl_add_u64 v[36:37], v[36:37], 0, s[8:9]
	v_lshlrev_b64 v[36:37], 12, v[36:37]
	v_lshl_add_u64 v[36:37], s[6:7], 0, v[36:37]
	v_lshl_add_u64 v[36:37], v[36:37], 0, v[72:73]
	v_lshl_add_u64 v[38:39], v[40:41], 0, v[152:153]
	v_mfma_f32_16x16x32_bf16 v[12:15], v[128:131], v[108:111], v[12:15]
	s_waitcnt vmcnt(15)
	v_pk_mul_f32 v[30:31], v[30:31], v[206:207]
	v_pk_mul_f32 v[28:29], v[28:29], v[204:205]
	global_store_dwordx4 v[36:37], v[28:31], off
	v_lshl_add_u64 v[32:33], v[40:41], 0, v[156:157]
	v_mfma_f32_16x16x32_bf16 v[12:15], v[132:135], v[64:67], v[12:15]
	s_waitcnt vmcnt(15)
	v_pk_mul_f32 v[26:27], v[26:27], v[210:211]
	v_pk_mul_f32 v[24:25], v[24:25], v[208:209]
	global_store_dwordx4 v[36:37], v[24:27], off offset:16
	v_lshl_add_u64 v[28:29], v[40:41], 0, v[158:159]
	v_mfma_f32_16x16x32_bf16 v[8:11], v[52:55], v[108:111], v[8:11]
	s_waitcnt vmcnt(15)
	v_pk_mul_f32 v[18:19], v[18:19], v[214:215]
	v_pk_mul_f32 v[16:17], v[16:17], v[212:213]
	global_store_dwordx4 v[36:37], v[16:19], off offset:128
	v_lshl_add_u64 v[24:25], v[40:41], 0, v[160:161]
	v_mfma_f32_16x16x32_bf16 v[8:11], v[56:59], v[64:67], v[8:11]
	s_waitcnt vmcnt(15)
	v_pk_mul_f32 v[14:15], v[14:15], v[218:219]
	v_pk_mul_f32 v[12:13], v[12:13], v[216:217]
	global_store_dwordx4 v[36:37], v[12:15], off offset:144
	v_lshl_add_u64 v[16:17], v[40:41], 0, v[162:163]
	v_mfma_f32_16x16x32_bf16 v[4:7], v[136:139], v[108:111], v[4:7]
	s_waitcnt vmcnt(15)
	v_pk_mul_f32 v[10:11], v[10:11], v[222:223]
	v_pk_mul_f32 v[8:9], v[8:9], v[220:221]
	global_store_dwordx4 v[36:37], v[8:11], off offset:256
	v_mfma_f32_16x16x32_bf16 v[4:7], v[140:143], v[64:67], v[4:7]
	v_lshl_add_u64 v[12:13], v[40:41], 0, v[164:165]
	v_mfma_f32_16x16x32_bf16 v[0:3], v[48:51], v[108:111], v[0:3]
	v_mfma_f32_16x16x32_bf16 v[0:3], v[44:47], v[64:67], v[0:3]
	s_waitcnt vmcnt(15)
	s_nop 3
	v_pk_mul_f32 v[6:7], v[6:7], v[226:227]
	v_pk_mul_f32 v[4:5], v[4:5], v[224:225]
	global_store_dwordx4 v[36:37], v[4:7], off offset:272
	v_lshl_add_u64 v[8:9], v[40:41], 0, v[166:167]
	v_mfma_f32_16x16x32_bf16 v[20:23], v[146:149], v[108:111], v[20:23]
	s_waitcnt vmcnt(15)
	v_pk_mul_f32 v[2:3], v[2:3], v[230:231]
	v_pk_mul_f32 v[0:1], v[0:1], v[228:229]
	global_store_dwordx4 v[36:37], v[0:3], off offset:384
	v_mfma_f32_16x16x32_bf16 v[4:7], v[104:107], v[64:67], v[20:23]
	s_waitcnt vmcnt(15)
	s_nop 6
	v_pk_mul_f32 v[234:235], v[6:7], v[234:235]
	v_pk_mul_f32 v[232:233], v[4:5], v[232:233]
	global_store_dwordx4 v[36:37], v[232:235], off offset:400
	s_cbranch_scc0 .LBB0_1090
